# k-inner MFMA order + hand-written mode-2 epilogue (16 residual loads in flight) + prep_row loads hoisted
# speedup vs baseline: 1.0027x; 1.0027x over previous
;     template <int MODE> __device__ __forceinline__ void run(const f32x4 (&acc)[2][2][4][2], const Unit& u, int wr, int wc, int fr, int fq) const {
;     ...
;                         const int row = row0 + ai * HALF + m * 16, col = u.pn * BM + bj * HALF + wc * 32 + 8 * fq;
;                         const size_t off = (size_t)row * ldc + col;
;                         f32x4 v0 = acc[ai][bj][m][0], v1 = acc[ai][bj][m][1];
;                         if constexpr (MODE == 0 || MODE == 6) { v0 = v0 * rsv; v1 = v1 * rsv; }
;                         if constexpr (MODE == 0) {
;                             u32x4 w; w.x = cvt_pk_bf16(v0[0], v0[1]); w.y = cvt_pk_bf16(v0[2], v0[3]); w.z = cvt_pk_bf16(v1[0], v1[1]); w.w = cvt_pk_bf16(v1[2], v1[3]);
;                             *(u32x4*)(bout + off) = w;
;                         } else if constexpr (MODE == 2) {
;                             const u32x4 xw = *(const u32x4*)(xin + off);
;                             v0[0] = bflo(xw.x) + v0[0] * alpha; v0[1] = bfhi(xw.x) + v0[1] * alpha; v0[2] = bflo(xw.y) + v0[2] * alpha; v0[3] = bfhi(xw.y) + v0[3] * alpha;
;                             v1[0] = bflo(xw.z) + v1[0] * alpha; v1[1] = bfhi(xw.z) + v1[1] * alpha; v1[2] = bflo(xw.w) + v1[2] * alpha; v1[3] = bfhi(xw.w) + v1[3] * alpha;
;                         } else if constexpr (MODE == 3 || MODE == 4) {
;                             const u32x4 gw = *(const u32x4*)(gate + (size_t)row * ldg + col);
;                             f32x4 s0, s1;
;                             s0[0] = sigm(bflo(gw.x)); s0[1] = sigm(bfhi(gw.x)); s0[2] = sigm(bflo(gw.y)); s0[3] = sigm(bfhi(gw.y));
;                             s1[0] = sigm(bflo(gw.z)); s1[1] = sigm(bfhi(gw.z)); s1[2] = sigm(bflo(gw.w)); s1[3] = sigm(bfhi(gw.w));
;                             v0 = v0 * s0; v1 = v1 * s1;
;                             if constexpr (MODE == 3) { u32x4 w; w.x = cvt_pk_bf16(v0[0], v0[1]); w.y = cvt_pk_bf16(v0[2], v0[3]); w.z = cvt_pk_bf16(v1[0], v1[1]); w.w = cvt_pk_bf16(v1[2], v1[3]); *(u32x4*)(tout + off) = w; }
;                             else {
;                                 { const u32x4 tw = *(const u32x4*)(tin + off); v0[0] += bflo(tw.x); v0[1] += bfhi(tw.x); v0[2] += bflo(tw.y); v0[3] += bfhi(tw.y); v1[0] += bflo(tw.z); v1[1] += bfhi(tw.z); v1[2] += bflo(tw.w); v1[3] += bfhi(tw.w); }
.LBB0_355:
	s_cmp_lt_i32 s3, 1
	s_mov_b64 s[0:1], -1
	s_cbranch_scc1 .LBB0_417
	s_cmp_gt_i32 s3, 1
	s_cbranch_scc0 .LBB0_414
	v_lshl_add_u32 v250, s92, 8, v179
	v_lshl_or_b32 v252, s47, 8, v155
	v_ashrrev_i32_e32 v251, 31, v250
	v_ashrrev_i32_e32 v253, 31, v252
	v_mul_lo_u32 v194, s60, v251
	s_waitcnt lgkmcnt(0)
	v_mad_u64_u32 v[198:199], s[0:1], s60, v250, v[252:253]
	v_mul_lo_u32 v195, s61, v250
	v_add3_u32 v199, v195, v199, v194
	v_lshlrev_b64 v[198:199], 1, v[198:199]
	v_lshl_add_u64 v[246:247], s[28:29], 0, v[198:199]
	v_lshl_add_u64 v[248:249], s[62:63], 0, v[198:199]
	s_lshl_b64 s[0:1], s[60:61], 5
	s_lshl_b64 s[12:13], s[0:1], 2
	s_add_u32 s12, s12, s0
	s_addc_u32 s13, s13, s1
	global_load_dwordx4 v[130:133], v[246:247], off
	global_load_dwordx4 v[134:137], v[246:247], off offset:256
	v_lshl_add_u64 v[246:247], v[246:247], 0, s[0:1]
	global_load_dwordx4 v[138:141], v[246:247], off
	global_load_dwordx4 v[142:145], v[246:247], off offset:256
	v_lshl_add_u64 v[246:247], v[246:247], 0, s[0:1]
	global_load_dwordx4 v[164:167], v[246:247], off
	global_load_dwordx4 v[184:187], v[246:247], off offset:256
	v_lshl_add_u64 v[246:247], v[246:247], 0, s[0:1]
	global_load_dwordx4 v[188:191], v[246:247], off
	global_load_dwordx4 v[200:203], v[246:247], off offset:256
	v_lshl_add_u64 v[246:247], v[246:247], 0, s[12:13]
	global_load_dwordx4 v[204:207], v[246:247], off
	global_load_dwordx4 v[208:211], v[246:247], off offset:256
	v_lshl_add_u64 v[246:247], v[246:247], 0, s[0:1]
	global_load_dwordx4 v[212:215], v[246:247], off
	global_load_dwordx4 v[216:219], v[246:247], off offset:256
	v_lshl_add_u64 v[246:247], v[246:247], 0, s[0:1]
	global_load_dwordx4 v[220:223], v[246:247], off
	global_load_dwordx4 v[226:229], v[246:247], off offset:256
	v_lshl_add_u64 v[246:247], v[246:247], 0, s[0:1]
	global_load_dwordx4 v[238:241], v[246:247], off
	global_load_dwordx4 v[242:245], v[246:247], off offset:256
	s_lshl_b32 s10, s47, 2
	s_ashr_i32 s11, s10, 31
	v_lshlrev_b64 v[168:169], 7, v[250:251]
	v_lshl_add_u64 v[168:169], s[58:59], 0, v[168:169]
	v_lshl_add_u64 v[168:169], s[10:11], 2, v[168:169]
	s_lshl_b32 s10, s38, 2
	s_mov_b32 s11, 0
	v_lshl_add_u64 v[168:169], v[168:169], 0, s[10:11]
	s_waitcnt vmcnt(15)
	v_lshlrev_b32_e32 v250, 16, v130
	v_and_b32_e32 v251, 0xffff0000, v130
	v_lshlrev_b32_e32 v252, 16, v131
	v_and_b32_e32 v253, 0xffff0000, v131
	v_lshlrev_b32_e32 v194, 16, v132
	v_and_b32_e32 v195, 0xffff0000, v132
	v_lshlrev_b32_e32 v198, 16, v133
	v_and_b32_e32 v199, 0xffff0000, v133
	v_pk_fma_f32 v[250:251], s[72:73], v[126:127], v[250:251]
	v_pk_fma_f32 v[252:253], s[72:73], v[128:129], v[252:253]
	v_pk_fma_f32 v[194:195], s[72:73], v[122:123], v[194:195]
	v_pk_fma_f32 v[198:199], s[72:73], v[124:125], v[198:199]
	v_cvt_pk_bf16_f32 v130, v250, v251
	v_cvt_pk_bf16_f32 v131, v252, v253
	v_cvt_pk_bf16_f32 v132, v194, v195
	v_cvt_pk_bf16_f32 v133, v198, v199
	global_store_dwordx4 v[248:249], v[130:133], off
	v_lshlrev_b32_e32 v250, 16, v130
	v_and_b32_e32 v251, 0xffff0000, v130
	v_lshlrev_b32_e32 v252, 16, v131
	v_and_b32_e32 v253, 0xffff0000, v131
	v_lshlrev_b32_e32 v194, 16, v132
	v_and_b32_e32 v195, 0xffff0000, v132
	v_lshlrev_b32_e32 v198, 16, v133
	v_and_b32_e32 v199, 0xffff0000, v133
	v_mul_f32_e32 v251, v251, v251
	v_fmac_f32_e32 v251, v250, v250
	v_mul_f32_e32 v253, v253, v253
	v_fmac_f32_e32 v253, v252, v252
	v_mul_f32_e32 v195, v195, v195
	v_fmac_f32_e32 v195, v194, v194
	v_mul_f32_e32 v199, v199, v199
	v_fmac_f32_e32 v199, v198, v198
	v_add_f32_e32 v251, v251, v253
	v_add_f32_e32 v195, v195, v199
	v_add_f32_e32 v130, v251, v195
	s_waitcnt vmcnt(15)
	v_lshlrev_b32_e32 v250, 16, v134
	v_and_b32_e32 v251, 0xffff0000, v134
	v_lshlrev_b32_e32 v252, 16, v135
	v_and_b32_e32 v253, 0xffff0000, v135
	v_lshlrev_b32_e32 v194, 16, v136
	v_and_b32_e32 v195, 0xffff0000, v136
	v_lshlrev_b32_e32 v198, 16, v137
	v_and_b32_e32 v199, 0xffff0000, v137
	v_pk_fma_f32 v[250:251], s[72:73], v[118:119], v[250:251]
	v_pk_fma_f32 v[252:253], s[72:73], v[120:121], v[252:253]
	v_pk_fma_f32 v[194:195], s[72:73], v[114:115], v[194:195]
	v_pk_fma_f32 v[198:199], s[72:73], v[116:117], v[198:199]
	v_cvt_pk_bf16_f32 v134, v250, v251
	v_cvt_pk_bf16_f32 v135, v252, v253
	v_cvt_pk_bf16_f32 v136, v194, v195
	v_cvt_pk_bf16_f32 v137, v198, v199
	global_store_dwordx4 v[248:249], v[134:137], off offset:256
	v_lshlrev_b32_e32 v250, 16, v134
	v_and_b32_e32 v251, 0xffff0000, v134
	v_lshlrev_b32_e32 v252, 16, v135
	v_and_b32_e32 v253, 0xffff0000, v135
	v_lshlrev_b32_e32 v194, 16, v136
	v_and_b32_e32 v195, 0xffff0000, v136
	v_lshlrev_b32_e32 v198, 16, v137
	v_and_b32_e32 v199, 0xffff0000, v137
	v_mul_f32_e32 v251, v251, v251
	v_fmac_f32_e32 v251, v250, v250
	v_mul_f32_e32 v253, v253, v253
	v_fmac_f32_e32 v253, v252, v252
	v_mul_f32_e32 v195, v195, v195
	v_fmac_f32_e32 v195, v194, v194
	v_mul_f32_e32 v199, v199, v199
	v_fmac_f32_e32 v199, v198, v198
	v_add_f32_e32 v251, v251, v253
	v_add_f32_e32 v195, v195, v199
	v_add_f32_e32 v251, v251, v195
	v_add_f32_e32 v130, v130, v251
	v_lshl_add_u64 v[248:249], v[248:249], 0, s[0:1]
	s_waitcnt vmcnt(15)
;     template <int MODE> __device__ __forceinline__ void run(const f32x4 (&acc)[2][2][4][2], const Unit& u, int wr, int wc, int fr, int fq) const {
;     ...
;                             const u32x4 xw = *(const u32x4*)(xin + off);
;                             v0[0] = bflo(xw.x) + v0[0] * alpha; v0[1] = bfhi(xw.x) + v0[1] * alpha; v0[2] = bflo(xw.y) + v0[2] * alpha; v0[3] = bfhi(xw.y) + v0[3] * alpha;
;                             v1[0] = bflo(xw.z) + v1[0] * alpha; v1[1] = bfhi(xw.z) + v1[1] * alpha; v1[2] = bflo(xw.w) + v1[2] * alpha; v1[3] = bfhi(xw.w) + v1[3] * alpha;
;                         } else if constexpr (MODE == 3 || MODE == 4) {
;                             const u32x4 gw = *(const u32x4*)(gate + (size_t)row * ldg + col);
;                             f32x4 s0, s1;
;                             s0[0] = sigm(bflo(gw.x)); s0[1] = sigm(bfhi(gw.x)); s0[2] = sigm(bflo(gw.y)); s0[3] = sigm(bfhi(gw.y));
;                             s1[0] = sigm(bflo(gw.z)); s1[1] = sigm(bfhi(gw.z)); s1[2] = sigm(bflo(gw.w)); s1[3] = sigm(bfhi(gw.w));
;                             v0 = v0 * s0; v1 = v1 * s1;
;                             if constexpr (MODE == 3) { u32x4 w; w.x = cvt_pk_bf16(v0[0], v0[1]); w.y = cvt_pk_bf16(v0[2], v0[3]); w.z = cvt_pk_bf16(v1[0], v1[1]); w.w = cvt_pk_bf16(v1[2], v1[3]); *(u32x4*)(tout + off) = w; }
;                             else {
;                                 { const u32x4 tw = *(const u32x4*)(tin + off); v0[0] += bflo(tw.x); v0[1] += bfhi(tw.x); v0[2] += bflo(tw.y); v0[3] += bfhi(tw.y); v1[0] += bflo(tw.z); v1[1] += bfhi(tw.z); v1[2] += bflo(tw.w); v1[3] += bfhi(tw.w); }
;                                 u32x4 w; w.x = cvt_pk_bf16(v0[0], v0[1]); w.y = cvt_pk_bf16(v0[2], v0[3]); w.z = cvt_pk_bf16(v1[0], v1[1]); w.w = cvt_pk_bf16(v1[2], v1[3]);
;                                 *(u32x4*)(bout + off) = w;
;                             }
;                         } else if constexpr (MODE == 5) {
;                             u32x4 w; w.x = cvt_pk_bf16(v0[0], v0[1]); w.y = cvt_pk_bf16(v0[2], v0[3]); w.z = cvt_pk_bf16(v1[0], v1[1]); w.w = cvt_pk_bf16(v1[2], v1[3]); *(u32x4*)(tout + off) = w;
;                         } else {
;                             const u32x4 tw = *(const u32x4*)(tin + off); const f32x4 p0 = {bflo(tw.x), bfhi(tw.x), bflo(tw.y), bfhi(tw.y)}, p1 = {bflo(tw.z), bfhi(tw.z), bflo(tw.w), bfhi(tw.w)};
	v_lshlrev_b32_e32 v250, 16, v138
	v_and_b32_e32 v251, 0xffff0000, v138
	v_lshlrev_b32_e32 v252, 16, v139
	v_and_b32_e32 v253, 0xffff0000, v139
	v_lshlrev_b32_e32 v194, 16, v140
	v_and_b32_e32 v195, 0xffff0000, v140
	v_lshlrev_b32_e32 v198, 16, v141
	v_and_b32_e32 v199, 0xffff0000, v141
	v_pk_fma_f32 v[250:251], s[72:73], v[110:111], v[250:251]
	v_pk_fma_f32 v[252:253], s[72:73], v[112:113], v[252:253]
	v_pk_fma_f32 v[194:195], s[72:73], v[106:107], v[194:195]
	v_pk_fma_f32 v[198:199], s[72:73], v[108:109], v[198:199]
	v_cvt_pk_bf16_f32 v138, v250, v251
	v_cvt_pk_bf16_f32 v139, v252, v253
	v_cvt_pk_bf16_f32 v140, v194, v195
	v_cvt_pk_bf16_f32 v141, v198, v199
	global_store_dwordx4 v[248:249], v[138:141], off
	v_lshlrev_b32_e32 v250, 16, v138
	v_and_b32_e32 v251, 0xffff0000, v138
	v_lshlrev_b32_e32 v252, 16, v139
	v_and_b32_e32 v253, 0xffff0000, v139
	v_lshlrev_b32_e32 v194, 16, v140
	v_and_b32_e32 v195, 0xffff0000, v140
	v_lshlrev_b32_e32 v198, 16, v141
	v_and_b32_e32 v199, 0xffff0000, v141
	v_mul_f32_e32 v251, v251, v251
	v_fmac_f32_e32 v251, v250, v250
	v_mul_f32_e32 v253, v253, v253
	v_fmac_f32_e32 v253, v252, v252
	v_mul_f32_e32 v195, v195, v195
	v_fmac_f32_e32 v195, v194, v194
	v_mul_f32_e32 v199, v199, v199
	v_fmac_f32_e32 v199, v198, v198
	v_add_f32_e32 v251, v251, v253
	v_add_f32_e32 v195, v195, v199
	v_add_f32_e32 v138, v251, v195
	s_waitcnt vmcnt(15)
	v_lshlrev_b32_e32 v250, 16, v142
	v_and_b32_e32 v251, 0xffff0000, v142
	v_lshlrev_b32_e32 v252, 16, v143
	v_and_b32_e32 v253, 0xffff0000, v143
	v_lshlrev_b32_e32 v194, 16, v144
	v_and_b32_e32 v195, 0xffff0000, v144
	v_lshlrev_b32_e32 v198, 16, v145
	v_and_b32_e32 v199, 0xffff0000, v145
	v_pk_fma_f32 v[250:251], s[72:73], v[102:103], v[250:251]
	v_pk_fma_f32 v[252:253], s[72:73], v[104:105], v[252:253]
	v_pk_fma_f32 v[194:195], s[72:73], v[98:99], v[194:195]
	v_pk_fma_f32 v[198:199], s[72:73], v[100:101], v[198:199]
	v_cvt_pk_bf16_f32 v142, v250, v251
	v_cvt_pk_bf16_f32 v143, v252, v253
	v_cvt_pk_bf16_f32 v144, v194, v195
	v_cvt_pk_bf16_f32 v145, v198, v199
	global_store_dwordx4 v[248:249], v[142:145], off offset:256
	v_lshlrev_b32_e32 v250, 16, v142
	v_and_b32_e32 v251, 0xffff0000, v142
	v_lshlrev_b32_e32 v252, 16, v143
	v_and_b32_e32 v253, 0xffff0000, v143
	v_lshlrev_b32_e32 v194, 16, v144
	v_and_b32_e32 v195, 0xffff0000, v144
	v_lshlrev_b32_e32 v198, 16, v145
	v_and_b32_e32 v199, 0xffff0000, v145
	v_mul_f32_e32 v251, v251, v251
	v_fmac_f32_e32 v251, v250, v250
	v_mul_f32_e32 v253, v253, v253
	v_fmac_f32_e32 v253, v252, v252
	v_mul_f32_e32 v195, v195, v195
	v_fmac_f32_e32 v195, v194, v194
	v_mul_f32_e32 v199, v199, v199
	v_fmac_f32_e32 v199, v198, v198
	v_add_f32_e32 v251, v251, v253
	v_add_f32_e32 v195, v195, v199
	v_add_f32_e32 v251, v251, v195
	v_add_f32_e32 v138, v138, v251
	v_lshl_add_u64 v[248:249], v[248:249], 0, s[0:1]
	s_waitcnt vmcnt(15)
	v_lshlrev_b32_e32 v250, 16, v164
	v_and_b32_e32 v251, 0xffff0000, v164
	v_lshlrev_b32_e32 v252, 16, v165
	v_and_b32_e32 v253, 0xffff0000, v165
	v_lshlrev_b32_e32 v194, 16, v166
	v_and_b32_e32 v195, 0xffff0000, v166
	v_lshlrev_b32_e32 v198, 16, v167
	v_and_b32_e32 v199, 0xffff0000, v167
	v_pk_fma_f32 v[250:251], s[72:73], v[94:95], v[250:251]
	v_pk_fma_f32 v[252:253], s[72:73], v[96:97], v[252:253]
	v_pk_fma_f32 v[194:195], s[72:73], v[90:91], v[194:195]
	v_pk_fma_f32 v[198:199], s[72:73], v[92:93], v[198:199]
	v_cvt_pk_bf16_f32 v164, v250, v251
	v_cvt_pk_bf16_f32 v165, v252, v253
	v_cvt_pk_bf16_f32 v166, v194, v195
	v_cvt_pk_bf16_f32 v167, v198, v199
	global_store_dwordx4 v[248:249], v[164:167], off
	v_lshlrev_b32_e32 v250, 16, v164
	v_and_b32_e32 v251, 0xffff0000, v164
	v_lshlrev_b32_e32 v252, 16, v165
	v_and_b32_e32 v253, 0xffff0000, v165
	v_lshlrev_b32_e32 v194, 16, v166
	v_and_b32_e32 v195, 0xffff0000, v166
	v_lshlrev_b32_e32 v198, 16, v167
	v_and_b32_e32 v199, 0xffff0000, v167
	v_mul_f32_e32 v251, v251, v251
	v_fmac_f32_e32 v251, v250, v250
	v_mul_f32_e32 v253, v253, v253
	v_fmac_f32_e32 v253, v252, v252
	v_mul_f32_e32 v195, v195, v195
	v_fmac_f32_e32 v195, v194, v194
	v_mul_f32_e32 v199, v199, v199
	v_fmac_f32_e32 v199, v198, v198
	v_add_f32_e32 v251, v251, v253
	v_add_f32_e32 v195, v195, v199
	v_add_f32_e32 v164, v251, v195
	s_waitcnt vmcnt(15)
	v_lshlrev_b32_e32 v250, 16, v184
	v_and_b32_e32 v251, 0xffff0000, v184
	v_lshlrev_b32_e32 v252, 16, v185
	v_and_b32_e32 v253, 0xffff0000, v185
	v_lshlrev_b32_e32 v194, 16, v186
	v_and_b32_e32 v195, 0xffff0000, v186
	v_lshlrev_b32_e32 v198, 16, v187
	v_and_b32_e32 v199, 0xffff0000, v187
	v_pk_fma_f32 v[250:251], s[72:73], v[86:87], v[250:251]
	v_pk_fma_f32 v[252:253], s[72:73], v[88:89], v[252:253]
	v_pk_fma_f32 v[194:195], s[72:73], v[82:83], v[194:195]
	v_pk_fma_f32 v[198:199], s[72:73], v[84:85], v[198:199]
	v_cvt_pk_bf16_f32 v184, v250, v251
	v_cvt_pk_bf16_f32 v185, v252, v253
	v_cvt_pk_bf16_f32 v186, v194, v195
	v_cvt_pk_bf16_f32 v187, v198, v199
	global_store_dwordx4 v[248:249], v[184:187], off offset:256
	v_lshlrev_b32_e32 v250, 16, v184
	v_and_b32_e32 v251, 0xffff0000, v184
	v_lshlrev_b32_e32 v252, 16, v185
	v_and_b32_e32 v253, 0xffff0000, v185
	v_lshlrev_b32_e32 v194, 16, v186
	v_and_b32_e32 v195, 0xffff0000, v186
	v_lshlrev_b32_e32 v198, 16, v187
	v_and_b32_e32 v199, 0xffff0000, v187
	v_mul_f32_e32 v251, v251, v251
	v_fmac_f32_e32 v251, v250, v250
	v_mul_f32_e32 v253, v253, v253
	v_fmac_f32_e32 v253, v252, v252
	v_mul_f32_e32 v195, v195, v195
	v_fmac_f32_e32 v195, v194, v194
	v_mul_f32_e32 v199, v199, v199
	v_fmac_f32_e32 v199, v198, v198
	v_add_f32_e32 v251, v251, v253
	v_add_f32_e32 v195, v195, v199
	v_add_f32_e32 v251, v251, v195
	v_add_f32_e32 v164, v164, v251
	v_lshl_add_u64 v[248:249], v[248:249], 0, s[0:1]
	s_waitcnt vmcnt(15)
;     template <int MODE> __device__ __forceinline__ void run(const f32x4 (&acc)[2][2][4][2], const Unit& u, int wr, int wc, int fr, int fq) const {
;     ...
;                             const u32x4 xw = *(const u32x4*)(xin + off);
;                             v0[0] = bflo(xw.x) + v0[0] * alpha; v0[1] = bfhi(xw.x) + v0[1] * alpha; v0[2] = bflo(xw.y) + v0[2] * alpha; v0[3] = bfhi(xw.y) + v0[3] * alpha;
;                             v1[0] = bflo(xw.z) + v1[0] * alpha; v1[1] = bfhi(xw.z) + v1[1] * alpha; v1[2] = bflo(xw.w) + v1[2] * alpha; v1[3] = bfhi(xw.w) + v1[3] * alpha;
;                         } else if constexpr (MODE == 3 || MODE == 4) {
;                             const u32x4 gw = *(const u32x4*)(gate + (size_t)row * ldg + col);
;                             f32x4 s0, s1;
;                             s0[0] = sigm(bflo(gw.x)); s0[1] = sigm(bfhi(gw.x)); s0[2] = sigm(bflo(gw.y)); s0[3] = sigm(bfhi(gw.y));
;                             s1[0] = sigm(bflo(gw.z)); s1[1] = sigm(bfhi(gw.z)); s1[2] = sigm(bflo(gw.w)); s1[3] = sigm(bfhi(gw.w));
;                             v0 = v0 * s0; v1 = v1 * s1;
;                             if constexpr (MODE == 3) { u32x4 w; w.x = cvt_pk_bf16(v0[0], v0[1]); w.y = cvt_pk_bf16(v0[2], v0[3]); w.z = cvt_pk_bf16(v1[0], v1[1]); w.w = cvt_pk_bf16(v1[2], v1[3]); *(u32x4*)(tout + off) = w; }
;                             else {
;                                 { const u32x4 tw = *(const u32x4*)(tin + off); v0[0] += bflo(tw.x); v0[1] += bfhi(tw.x); v0[2] += bflo(tw.y); v0[3] += bfhi(tw.y); v1[0] += bflo(tw.z); v1[1] += bfhi(tw.z); v1[2] += bflo(tw.w); v1[3] += bfhi(tw.w); }
;                                 u32x4 w; w.x = cvt_pk_bf16(v0[0], v0[1]); w.y = cvt_pk_bf16(v0[2], v0[3]); w.z = cvt_pk_bf16(v1[0], v1[1]); w.w = cvt_pk_bf16(v1[2], v1[3]);
;                                 *(u32x4*)(bout + off) = w;
;                             }
;                         } else if constexpr (MODE == 5) {
;                             u32x4 w; w.x = cvt_pk_bf16(v0[0], v0[1]); w.y = cvt_pk_bf16(v0[2], v0[3]); w.z = cvt_pk_bf16(v1[0], v1[1]); w.w = cvt_pk_bf16(v1[2], v1[3]); *(u32x4*)(tout + off) = w;
;                         } else {
;                             const u32x4 tw = *(const u32x4*)(tin + off); const f32x4 p0 = {bflo(tw.x), bfhi(tw.x), bflo(tw.y), bfhi(tw.y)}, p1 = {bflo(tw.z), bfhi(tw.z), bflo(tw.w), bfhi(tw.w)};
	v_lshlrev_b32_e32 v250, 16, v188
	v_and_b32_e32 v251, 0xffff0000, v188
	v_lshlrev_b32_e32 v252, 16, v189
	v_and_b32_e32 v253, 0xffff0000, v189
	v_lshlrev_b32_e32 v194, 16, v190
	v_and_b32_e32 v195, 0xffff0000, v190
	v_lshlrev_b32_e32 v198, 16, v191
	v_and_b32_e32 v199, 0xffff0000, v191
	v_pk_fma_f32 v[250:251], s[72:73], v[78:79], v[250:251]
	v_pk_fma_f32 v[252:253], s[72:73], v[80:81], v[252:253]
	v_pk_fma_f32 v[194:195], s[72:73], v[74:75], v[194:195]
	v_pk_fma_f32 v[198:199], s[72:73], v[76:77], v[198:199]
	v_cvt_pk_bf16_f32 v188, v250, v251
	v_cvt_pk_bf16_f32 v189, v252, v253
	v_cvt_pk_bf16_f32 v190, v194, v195
	v_cvt_pk_bf16_f32 v191, v198, v199
	global_store_dwordx4 v[248:249], v[188:191], off
	v_lshlrev_b32_e32 v250, 16, v188
	v_and_b32_e32 v251, 0xffff0000, v188
	v_lshlrev_b32_e32 v252, 16, v189
	v_and_b32_e32 v253, 0xffff0000, v189
	v_lshlrev_b32_e32 v194, 16, v190
	v_and_b32_e32 v195, 0xffff0000, v190
	v_lshlrev_b32_e32 v198, 16, v191
	v_and_b32_e32 v199, 0xffff0000, v191
	v_mul_f32_e32 v251, v251, v251
	v_fmac_f32_e32 v251, v250, v250
	v_mul_f32_e32 v253, v253, v253
	v_fmac_f32_e32 v253, v252, v252
	v_mul_f32_e32 v195, v195, v195
	v_fmac_f32_e32 v195, v194, v194
	v_mul_f32_e32 v199, v199, v199
	v_fmac_f32_e32 v199, v198, v198
	v_add_f32_e32 v251, v251, v253
	v_add_f32_e32 v195, v195, v199
	v_add_f32_e32 v188, v251, v195
	s_waitcnt vmcnt(15)
	v_lshlrev_b32_e32 v250, 16, v200
	v_and_b32_e32 v251, 0xffff0000, v200
	v_lshlrev_b32_e32 v252, 16, v201
	v_and_b32_e32 v253, 0xffff0000, v201
	v_lshlrev_b32_e32 v194, 16, v202
	v_and_b32_e32 v195, 0xffff0000, v202
	v_lshlrev_b32_e32 v198, 16, v203
	v_and_b32_e32 v199, 0xffff0000, v203
	v_pk_fma_f32 v[250:251], s[72:73], v[70:71], v[250:251]
	v_pk_fma_f32 v[252:253], s[72:73], v[72:73], v[252:253]
	v_pk_fma_f32 v[194:195], s[72:73], v[66:67], v[194:195]
	v_pk_fma_f32 v[198:199], s[72:73], v[68:69], v[198:199]
	v_cvt_pk_bf16_f32 v200, v250, v251
	v_cvt_pk_bf16_f32 v201, v252, v253
	v_cvt_pk_bf16_f32 v202, v194, v195
	v_cvt_pk_bf16_f32 v203, v198, v199
	global_store_dwordx4 v[248:249], v[200:203], off offset:256
	v_lshlrev_b32_e32 v250, 16, v200
	v_and_b32_e32 v251, 0xffff0000, v200
	v_lshlrev_b32_e32 v252, 16, v201
	v_and_b32_e32 v253, 0xffff0000, v201
	v_lshlrev_b32_e32 v194, 16, v202
	v_and_b32_e32 v195, 0xffff0000, v202
	v_lshlrev_b32_e32 v198, 16, v203
	v_and_b32_e32 v199, 0xffff0000, v203
	v_mul_f32_e32 v251, v251, v251
	v_fmac_f32_e32 v251, v250, v250
	v_mul_f32_e32 v253, v253, v253
	v_fmac_f32_e32 v253, v252, v252
	v_mul_f32_e32 v195, v195, v195
	v_fmac_f32_e32 v195, v194, v194
	v_mul_f32_e32 v199, v199, v199
	v_fmac_f32_e32 v199, v198, v198
	v_add_f32_e32 v251, v251, v253
	v_add_f32_e32 v195, v195, v199
	v_add_f32_e32 v251, v251, v195
	v_add_f32_e32 v188, v188, v251
	v_lshl_add_u64 v[248:249], v[248:249], 0, s[12:13]
	s_waitcnt vmcnt(15)
	v_lshlrev_b32_e32 v250, 16, v204
	v_and_b32_e32 v251, 0xffff0000, v204
	v_lshlrev_b32_e32 v252, 16, v205
	v_and_b32_e32 v253, 0xffff0000, v205
	v_lshlrev_b32_e32 v194, 16, v206
	v_and_b32_e32 v195, 0xffff0000, v206
	v_lshlrev_b32_e32 v198, 16, v207
	v_and_b32_e32 v199, 0xffff0000, v207
	v_pk_fma_f32 v[250:251], s[72:73], v[62:63], v[250:251]
	v_pk_fma_f32 v[252:253], s[72:73], v[64:65], v[252:253]
	v_pk_fma_f32 v[194:195], s[72:73], v[58:59], v[194:195]
	v_pk_fma_f32 v[198:199], s[72:73], v[60:61], v[198:199]
	v_cvt_pk_bf16_f32 v204, v250, v251
	v_cvt_pk_bf16_f32 v205, v252, v253
	v_cvt_pk_bf16_f32 v206, v194, v195
	v_cvt_pk_bf16_f32 v207, v198, v199
	global_store_dwordx4 v[248:249], v[204:207], off
	v_lshlrev_b32_e32 v250, 16, v204
	v_and_b32_e32 v251, 0xffff0000, v204
	v_lshlrev_b32_e32 v252, 16, v205
	v_and_b32_e32 v253, 0xffff0000, v205
	v_lshlrev_b32_e32 v194, 16, v206
	v_and_b32_e32 v195, 0xffff0000, v206
	v_lshlrev_b32_e32 v198, 16, v207
	v_and_b32_e32 v199, 0xffff0000, v207
	v_mul_f32_e32 v251, v251, v251
	v_fmac_f32_e32 v251, v250, v250
	v_mul_f32_e32 v253, v253, v253
	v_fmac_f32_e32 v253, v252, v252
	v_mul_f32_e32 v195, v195, v195
	v_fmac_f32_e32 v195, v194, v194
	v_mul_f32_e32 v199, v199, v199
	v_fmac_f32_e32 v199, v198, v198
	v_add_f32_e32 v251, v251, v253
	v_add_f32_e32 v195, v195, v199
	v_add_f32_e32 v204, v251, v195
	s_waitcnt vmcnt(15)
	v_lshlrev_b32_e32 v250, 16, v208
	v_and_b32_e32 v251, 0xffff0000, v208
	v_lshlrev_b32_e32 v252, 16, v209
	v_and_b32_e32 v253, 0xffff0000, v209
	v_lshlrev_b32_e32 v194, 16, v210
	v_and_b32_e32 v195, 0xffff0000, v210
	v_lshlrev_b32_e32 v198, 16, v211
	v_and_b32_e32 v199, 0xffff0000, v211
	v_pk_fma_f32 v[250:251], s[72:73], v[54:55], v[250:251]
	v_pk_fma_f32 v[252:253], s[72:73], v[56:57], v[252:253]
	v_pk_fma_f32 v[194:195], s[72:73], v[50:51], v[194:195]
	v_pk_fma_f32 v[198:199], s[72:73], v[52:53], v[198:199]
	v_cvt_pk_bf16_f32 v208, v250, v251
	v_cvt_pk_bf16_f32 v209, v252, v253
	v_cvt_pk_bf16_f32 v210, v194, v195
	v_cvt_pk_bf16_f32 v211, v198, v199
	global_store_dwordx4 v[248:249], v[208:211], off offset:256
	v_lshlrev_b32_e32 v250, 16, v208
	v_and_b32_e32 v251, 0xffff0000, v208
	v_lshlrev_b32_e32 v252, 16, v209
	v_and_b32_e32 v253, 0xffff0000, v209
	v_lshlrev_b32_e32 v194, 16, v210
	v_and_b32_e32 v195, 0xffff0000, v210
	v_lshlrev_b32_e32 v198, 16, v211
	v_and_b32_e32 v199, 0xffff0000, v211
	v_mul_f32_e32 v251, v251, v251
	v_fmac_f32_e32 v251, v250, v250
	v_mul_f32_e32 v253, v253, v253
	v_fmac_f32_e32 v253, v252, v252
	v_mul_f32_e32 v195, v195, v195
	v_fmac_f32_e32 v195, v194, v194
	v_mul_f32_e32 v199, v199, v199
	v_fmac_f32_e32 v199, v198, v198
	v_add_f32_e32 v251, v251, v253
	v_add_f32_e32 v195, v195, v199
	v_add_f32_e32 v251, v251, v195
	v_add_f32_e32 v204, v204, v251
	v_lshl_add_u64 v[248:249], v[248:249], 0, s[0:1]
	s_waitcnt vmcnt(15)
;     template <int MODE> __device__ __forceinline__ void run(const f32x4 (&acc)[2][2][4][2], const Unit& u, int wr, int wc, int fr, int fq) const {
;     ...
;                             const u32x4 xw = *(const u32x4*)(xin + off);
;                             v0[0] = bflo(xw.x) + v0[0] * alpha; v0[1] = bfhi(xw.x) + v0[1] * alpha; v0[2] = bflo(xw.y) + v0[2] * alpha; v0[3] = bfhi(xw.y) + v0[3] * alpha;
;                             v1[0] = bflo(xw.z) + v1[0] * alpha; v1[1] = bfhi(xw.z) + v1[1] * alpha; v1[2] = bflo(xw.w) + v1[2] * alpha; v1[3] = bfhi(xw.w) + v1[3] * alpha;
;                         } else if constexpr (MODE == 3 || MODE == 4) {
;                             const u32x4 gw = *(const u32x4*)(gate + (size_t)row * ldg + col);
;                             f32x4 s0, s1;
;                             s0[0] = sigm(bflo(gw.x)); s0[1] = sigm(bfhi(gw.x)); s0[2] = sigm(bflo(gw.y)); s0[3] = sigm(bfhi(gw.y));
;                             s1[0] = sigm(bflo(gw.z)); s1[1] = sigm(bfhi(gw.z)); s1[2] = sigm(bflo(gw.w)); s1[3] = sigm(bfhi(gw.w));
;                             v0 = v0 * s0; v1 = v1 * s1;
;                             if constexpr (MODE == 3) { u32x4 w; w.x = cvt_pk_bf16(v0[0], v0[1]); w.y = cvt_pk_bf16(v0[2], v0[3]); w.z = cvt_pk_bf16(v1[0], v1[1]); w.w = cvt_pk_bf16(v1[2], v1[3]); *(u32x4*)(tout + off) = w; }
;                             else {
;                                 { const u32x4 tw = *(const u32x4*)(tin + off); v0[0] += bflo(tw.x); v0[1] += bfhi(tw.x); v0[2] += bflo(tw.y); v0[3] += bfhi(tw.y); v1[0] += bflo(tw.z); v1[1] += bfhi(tw.z); v1[2] += bflo(tw.w); v1[3] += bfhi(tw.w); }
;                                 u32x4 w; w.x = cvt_pk_bf16(v0[0], v0[1]); w.y = cvt_pk_bf16(v0[2], v0[3]); w.z = cvt_pk_bf16(v1[0], v1[1]); w.w = cvt_pk_bf16(v1[2], v1[3]);
;                                 *(u32x4*)(bout + off) = w;
;                             }
;                         } else if constexpr (MODE == 5) {
;                             u32x4 w; w.x = cvt_pk_bf16(v0[0], v0[1]); w.y = cvt_pk_bf16(v0[2], v0[3]); w.z = cvt_pk_bf16(v1[0], v1[1]); w.w = cvt_pk_bf16(v1[2], v1[3]); *(u32x4*)(tout + off) = w;
;                         } else {
;                             const u32x4 tw = *(const u32x4*)(tin + off); const f32x4 p0 = {bflo(tw.x), bfhi(tw.x), bflo(tw.y), bfhi(tw.y)}, p1 = {bflo(tw.z), bfhi(tw.z), bflo(tw.w), bfhi(tw.w)};
	v_lshlrev_b32_e32 v250, 16, v212
	v_and_b32_e32 v251, 0xffff0000, v212
	v_lshlrev_b32_e32 v252, 16, v213
	v_and_b32_e32 v253, 0xffff0000, v213
	v_lshlrev_b32_e32 v194, 16, v214
	v_and_b32_e32 v195, 0xffff0000, v214
	v_lshlrev_b32_e32 v198, 16, v215
	v_and_b32_e32 v199, 0xffff0000, v215
	v_pk_fma_f32 v[250:251], s[72:73], v[46:47], v[250:251]
	v_pk_fma_f32 v[252:253], s[72:73], v[48:49], v[252:253]
	v_pk_fma_f32 v[194:195], s[72:73], v[42:43], v[194:195]
	v_pk_fma_f32 v[198:199], s[72:73], v[44:45], v[198:199]
	v_cvt_pk_bf16_f32 v212, v250, v251
	v_cvt_pk_bf16_f32 v213, v252, v253
	v_cvt_pk_bf16_f32 v214, v194, v195
	v_cvt_pk_bf16_f32 v215, v198, v199
	global_store_dwordx4 v[248:249], v[212:215], off
	v_lshlrev_b32_e32 v250, 16, v212
	v_and_b32_e32 v251, 0xffff0000, v212
	v_lshlrev_b32_e32 v252, 16, v213
	v_and_b32_e32 v253, 0xffff0000, v213
	v_lshlrev_b32_e32 v194, 16, v214
	v_and_b32_e32 v195, 0xffff0000, v214
	v_lshlrev_b32_e32 v198, 16, v215
	v_and_b32_e32 v199, 0xffff0000, v215
	v_mul_f32_e32 v251, v251, v251
	v_fmac_f32_e32 v251, v250, v250
	v_mul_f32_e32 v253, v253, v253
	v_fmac_f32_e32 v253, v252, v252
	v_mul_f32_e32 v195, v195, v195
	v_fmac_f32_e32 v195, v194, v194
	v_mul_f32_e32 v199, v199, v199
	v_fmac_f32_e32 v199, v198, v198
	v_add_f32_e32 v251, v251, v253
	v_add_f32_e32 v195, v195, v199
	v_add_f32_e32 v212, v251, v195
	s_waitcnt vmcnt(15)
	v_lshlrev_b32_e32 v250, 16, v216
	v_and_b32_e32 v251, 0xffff0000, v216
	v_lshlrev_b32_e32 v252, 16, v217
	v_and_b32_e32 v253, 0xffff0000, v217
	v_lshlrev_b32_e32 v194, 16, v218
	v_and_b32_e32 v195, 0xffff0000, v218
	v_lshlrev_b32_e32 v198, 16, v219
	v_and_b32_e32 v199, 0xffff0000, v219
	v_pk_fma_f32 v[250:251], s[72:73], v[38:39], v[250:251]
	v_pk_fma_f32 v[252:253], s[72:73], v[40:41], v[252:253]
	v_pk_fma_f32 v[194:195], s[72:73], v[34:35], v[194:195]
	v_pk_fma_f32 v[198:199], s[72:73], v[36:37], v[198:199]
	v_cvt_pk_bf16_f32 v216, v250, v251
	v_cvt_pk_bf16_f32 v217, v252, v253
	v_cvt_pk_bf16_f32 v218, v194, v195
	v_cvt_pk_bf16_f32 v219, v198, v199
	global_store_dwordx4 v[248:249], v[216:219], off offset:256
	v_lshlrev_b32_e32 v250, 16, v216
	v_and_b32_e32 v251, 0xffff0000, v216
	v_lshlrev_b32_e32 v252, 16, v217
	v_and_b32_e32 v253, 0xffff0000, v217
	v_lshlrev_b32_e32 v194, 16, v218
	v_and_b32_e32 v195, 0xffff0000, v218
	v_lshlrev_b32_e32 v198, 16, v219
	v_and_b32_e32 v199, 0xffff0000, v219
	v_mul_f32_e32 v251, v251, v251
	v_fmac_f32_e32 v251, v250, v250
	v_mul_f32_e32 v253, v253, v253
	v_fmac_f32_e32 v253, v252, v252
	v_mul_f32_e32 v195, v195, v195
	v_fmac_f32_e32 v195, v194, v194
	v_mul_f32_e32 v199, v199, v199
	v_fmac_f32_e32 v199, v198, v198
	v_add_f32_e32 v251, v251, v253
	v_add_f32_e32 v195, v195, v199
	v_add_f32_e32 v251, v251, v195
	v_add_f32_e32 v212, v212, v251
	v_lshl_add_u64 v[248:249], v[248:249], 0, s[0:1]
	s_waitcnt vmcnt(15)
	v_lshlrev_b32_e32 v250, 16, v220
	v_and_b32_e32 v251, 0xffff0000, v220
	v_lshlrev_b32_e32 v252, 16, v221
	v_and_b32_e32 v253, 0xffff0000, v221
	v_lshlrev_b32_e32 v194, 16, v222
	v_and_b32_e32 v195, 0xffff0000, v222
	v_lshlrev_b32_e32 v198, 16, v223
	v_and_b32_e32 v199, 0xffff0000, v223
	v_pk_fma_f32 v[250:251], s[72:73], v[30:31], v[250:251]
	v_pk_fma_f32 v[252:253], s[72:73], v[32:33], v[252:253]
	v_pk_fma_f32 v[194:195], s[72:73], v[26:27], v[194:195]
	v_pk_fma_f32 v[198:199], s[72:73], v[28:29], v[198:199]
	v_cvt_pk_bf16_f32 v220, v250, v251
	v_cvt_pk_bf16_f32 v221, v252, v253
	v_cvt_pk_bf16_f32 v222, v194, v195
	v_cvt_pk_bf16_f32 v223, v198, v199
	global_store_dwordx4 v[248:249], v[220:223], off
	v_lshlrev_b32_e32 v250, 16, v220
	v_and_b32_e32 v251, 0xffff0000, v220
	v_lshlrev_b32_e32 v252, 16, v221
	v_and_b32_e32 v253, 0xffff0000, v221
	v_lshlrev_b32_e32 v194, 16, v222
	v_and_b32_e32 v195, 0xffff0000, v222
	v_lshlrev_b32_e32 v198, 16, v223
	v_and_b32_e32 v199, 0xffff0000, v223
	v_mul_f32_e32 v251, v251, v251
	v_fmac_f32_e32 v251, v250, v250
	v_mul_f32_e32 v253, v253, v253
	v_fmac_f32_e32 v253, v252, v252
	v_mul_f32_e32 v195, v195, v195
	v_fmac_f32_e32 v195, v194, v194
	v_mul_f32_e32 v199, v199, v199
	v_fmac_f32_e32 v199, v198, v198
	v_add_f32_e32 v251, v251, v253
	v_add_f32_e32 v195, v195, v199
	v_add_f32_e32 v220, v251, v195
	s_waitcnt vmcnt(15)
	v_lshlrev_b32_e32 v250, 16, v226
	v_and_b32_e32 v251, 0xffff0000, v226
	v_lshlrev_b32_e32 v252, 16, v227
	v_and_b32_e32 v253, 0xffff0000, v227
	v_lshlrev_b32_e32 v194, 16, v228
	v_and_b32_e32 v195, 0xffff0000, v228
	v_lshlrev_b32_e32 v198, 16, v229
	v_and_b32_e32 v199, 0xffff0000, v229
	v_pk_fma_f32 v[250:251], s[72:73], v[22:23], v[250:251]
	v_pk_fma_f32 v[252:253], s[72:73], v[24:25], v[252:253]
	v_pk_fma_f32 v[194:195], s[72:73], v[18:19], v[194:195]
	v_pk_fma_f32 v[198:199], s[72:73], v[20:21], v[198:199]
	v_cvt_pk_bf16_f32 v226, v250, v251
	v_cvt_pk_bf16_f32 v227, v252, v253
	v_cvt_pk_bf16_f32 v228, v194, v195
	v_cvt_pk_bf16_f32 v229, v198, v199
	global_store_dwordx4 v[248:249], v[226:229], off offset:256
	v_lshlrev_b32_e32 v250, 16, v226
	v_and_b32_e32 v251, 0xffff0000, v226
	v_lshlrev_b32_e32 v252, 16, v227
	v_and_b32_e32 v253, 0xffff0000, v227
	v_lshlrev_b32_e32 v194, 16, v228
	v_and_b32_e32 v195, 0xffff0000, v228
	v_lshlrev_b32_e32 v198, 16, v229
	v_and_b32_e32 v199, 0xffff0000, v229
	v_mul_f32_e32 v251, v251, v251
	v_fmac_f32_e32 v251, v250, v250
	v_mul_f32_e32 v253, v253, v253
	v_fmac_f32_e32 v253, v252, v252
	v_mul_f32_e32 v195, v195, v195
	v_fmac_f32_e32 v195, v194, v194
	v_mul_f32_e32 v199, v199, v199
	v_fmac_f32_e32 v199, v198, v198
	v_add_f32_e32 v251, v251, v253
	v_add_f32_e32 v195, v195, v199
	v_add_f32_e32 v251, v251, v195
	v_add_f32_e32 v220, v220, v251
	v_lshl_add_u64 v[248:249], v[248:249], 0, s[0:1]
	s_waitcnt vmcnt(15)
;     template <int MODE> __device__ __forceinline__ void run(const f32x4 (&acc)[2][2][4][2], const Unit& u, int wr, int wc, int fr, int fq) const {
;     ...
;                             const u32x4 xw = *(const u32x4*)(xin + off);
;                             v0[0] = bflo(xw.x) + v0[0] * alpha; v0[1] = bfhi(xw.x) + v0[1] * alpha; v0[2] = bflo(xw.y) + v0[2] * alpha; v0[3] = bfhi(xw.y) + v0[3] * alpha;
;                             v1[0] = bflo(xw.z) + v1[0] * alpha; v1[1] = bfhi(xw.z) + v1[1] * alpha; v1[2] = bflo(xw.w) + v1[2] * alpha; v1[3] = bfhi(xw.w) + v1[3] * alpha;
;                         } else if constexpr (MODE == 3 || MODE == 4) {
;                             const u32x4 gw = *(const u32x4*)(gate + (size_t)row * ldg + col);
;                             f32x4 s0, s1;
;                             s0[0] = sigm(bflo(gw.x)); s0[1] = sigm(bfhi(gw.x)); s0[2] = sigm(bflo(gw.y)); s0[3] = sigm(bfhi(gw.y));
;                             s1[0] = sigm(bflo(gw.z)); s1[1] = sigm(bfhi(gw.z)); s1[2] = sigm(bflo(gw.w)); s1[3] = sigm(bfhi(gw.w));
;                             v0 = v0 * s0; v1 = v1 * s1;
;                             if constexpr (MODE == 3) { u32x4 w; w.x = cvt_pk_bf16(v0[0], v0[1]); w.y = cvt_pk_bf16(v0[2], v0[3]); w.z = cvt_pk_bf16(v1[0], v1[1]); w.w = cvt_pk_bf16(v1[2], v1[3]); *(u32x4*)(tout + off) = w; }
;                             else {
;                                 { const u32x4 tw = *(const u32x4*)(tin + off); v0[0] += bflo(tw.x); v0[1] += bfhi(tw.x); v0[2] += bflo(tw.y); v0[3] += bfhi(tw.y); v1[0] += bflo(tw.z); v1[1] += bfhi(tw.z); v1[2] += bflo(tw.w); v1[3] += bfhi(tw.w); }
;                                 u32x4 w; w.x = cvt_pk_bf16(v0[0], v0[1]); w.y = cvt_pk_bf16(v0[2], v0[3]); w.z = cvt_pk_bf16(v1[0], v1[1]); w.w = cvt_pk_bf16(v1[2], v1[3]);
;                                 *(u32x4*)(bout + off) = w;
;                             }
;                         } else if constexpr (MODE == 5) {
;                             u32x4 w; w.x = cvt_pk_bf16(v0[0], v0[1]); w.y = cvt_pk_bf16(v0[2], v0[3]); w.z = cvt_pk_bf16(v1[0], v1[1]); w.w = cvt_pk_bf16(v1[2], v1[3]); *(u32x4*)(tout + off) = w;
;                         } else {
;                             const u32x4 tw = *(const u32x4*)(tin + off); const f32x4 p0 = {bflo(tw.x), bfhi(tw.x), bflo(tw.y), bfhi(tw.y)}, p1 = {bflo(tw.z), bfhi(tw.z), bflo(tw.w), bfhi(tw.w)};
	v_lshlrev_b32_e32 v250, 16, v238
	v_and_b32_e32 v251, 0xffff0000, v238
	v_lshlrev_b32_e32 v252, 16, v239
	v_and_b32_e32 v253, 0xffff0000, v239
	v_lshlrev_b32_e32 v194, 16, v240
	v_and_b32_e32 v195, 0xffff0000, v240
	v_lshlrev_b32_e32 v198, 16, v241
	v_and_b32_e32 v199, 0xffff0000, v241
	v_pk_fma_f32 v[250:251], s[72:73], v[14:15], v[250:251]
	v_pk_fma_f32 v[252:253], s[72:73], v[16:17], v[252:253]
	v_pk_fma_f32 v[194:195], s[72:73], v[10:11], v[194:195]
	v_pk_fma_f32 v[198:199], s[72:73], v[12:13], v[198:199]
	v_cvt_pk_bf16_f32 v238, v250, v251
	v_cvt_pk_bf16_f32 v239, v252, v253
	v_cvt_pk_bf16_f32 v240, v194, v195
	v_cvt_pk_bf16_f32 v241, v198, v199
	global_store_dwordx4 v[248:249], v[238:241], off
	v_lshlrev_b32_e32 v250, 16, v238
	v_and_b32_e32 v251, 0xffff0000, v238
	v_lshlrev_b32_e32 v252, 16, v239
	v_and_b32_e32 v253, 0xffff0000, v239
	v_lshlrev_b32_e32 v194, 16, v240
	v_and_b32_e32 v195, 0xffff0000, v240
	v_lshlrev_b32_e32 v198, 16, v241
	v_and_b32_e32 v199, 0xffff0000, v241
	v_mul_f32_e32 v251, v251, v251
	v_fmac_f32_e32 v251, v250, v250
	v_mul_f32_e32 v253, v253, v253
	v_fmac_f32_e32 v253, v252, v252
	v_mul_f32_e32 v195, v195, v195
	v_fmac_f32_e32 v195, v194, v194
	v_mul_f32_e32 v199, v199, v199
	v_fmac_f32_e32 v199, v198, v198
	v_add_f32_e32 v251, v251, v253
	v_add_f32_e32 v195, v195, v199
	v_add_f32_e32 v238, v251, v195
	s_waitcnt vmcnt(15)
	v_lshlrev_b32_e32 v250, 16, v242
	v_and_b32_e32 v251, 0xffff0000, v242
	v_lshlrev_b32_e32 v252, 16, v243
	v_and_b32_e32 v253, 0xffff0000, v243
	v_lshlrev_b32_e32 v194, 16, v244
	v_and_b32_e32 v195, 0xffff0000, v244
	v_lshlrev_b32_e32 v198, 16, v245
	v_and_b32_e32 v199, 0xffff0000, v245
	v_pk_fma_f32 v[250:251], s[72:73], v[6:7], v[250:251]
	v_pk_fma_f32 v[252:253], s[72:73], v[8:9], v[252:253]
	v_pk_fma_f32 v[194:195], s[72:73], v[2:3], v[194:195]
	v_pk_fma_f32 v[198:199], s[72:73], v[4:5], v[198:199]
	v_cvt_pk_bf16_f32 v242, v250, v251
	v_cvt_pk_bf16_f32 v243, v252, v253
	v_cvt_pk_bf16_f32 v244, v194, v195
	v_cvt_pk_bf16_f32 v245, v198, v199
	global_store_dwordx4 v[248:249], v[242:245], off offset:256
	v_lshlrev_b32_e32 v250, 16, v242
	v_and_b32_e32 v251, 0xffff0000, v242
	v_lshlrev_b32_e32 v252, 16, v243
	v_and_b32_e32 v253, 0xffff0000, v243
	v_lshlrev_b32_e32 v194, 16, v244
	v_and_b32_e32 v195, 0xffff0000, v244
	v_lshlrev_b32_e32 v198, 16, v245
	v_and_b32_e32 v199, 0xffff0000, v245
	v_mul_f32_e32 v251, v251, v251
	v_fmac_f32_e32 v251, v250, v250
	v_mul_f32_e32 v253, v253, v253
	v_fmac_f32_e32 v253, v252, v252
	v_mul_f32_e32 v195, v195, v195
	v_fmac_f32_e32 v195, v194, v194
	v_mul_f32_e32 v199, v199, v199
	v_fmac_f32_e32 v199, v198, v198
	v_add_f32_e32 v251, v251, v253
	v_add_f32_e32 v195, v195, v199
	v_add_f32_e32 v251, v251, v195
	v_add_f32_e32 v238, v238, v251
	v_cmp_lt_i32_e32 vcc, v230, v225
	s_nop 0
	v_cndmask_b32_e32 v183, v224, v230, vcc
	v_cmp_lt_i32_e32 vcc, v231, v225
	v_lshlrev_b32_e32 v183, 2, v183
	v_cndmask_b32_e32 v250, v224, v231, vcc
	v_lshlrev_b32_e32 v250, 2, v250
	ds_bpermute_b32 v134, v183, v130
	ds_bpermute_b32 v142, v183, v138
	ds_bpermute_b32 v184, v183, v164
	ds_bpermute_b32 v200, v183, v188
	ds_bpermute_b32 v208, v183, v204
	ds_bpermute_b32 v216, v183, v212
	ds_bpermute_b32 v226, v183, v220
	ds_bpermute_b32 v242, v183, v238
	s_waitcnt lgkmcnt(7)
	v_add_f32_e32 v130, v130, v134
	s_waitcnt lgkmcnt(6)
	v_add_f32_e32 v138, v138, v142
	s_waitcnt lgkmcnt(5)
	v_add_f32_e32 v164, v164, v184
	s_waitcnt lgkmcnt(4)
	v_add_f32_e32 v188, v188, v200
	s_waitcnt lgkmcnt(3)
	v_add_f32_e32 v204, v204, v208
	s_waitcnt lgkmcnt(2)
	v_add_f32_e32 v212, v212, v216
	s_waitcnt lgkmcnt(1)
	v_add_f32_e32 v220, v220, v226
	s_waitcnt lgkmcnt(0)
	v_add_f32_e32 v238, v238, v242
	ds_bpermute_b32 v134, v250, v130
	ds_bpermute_b32 v142, v250, v138
	ds_bpermute_b32 v184, v250, v164
	ds_bpermute_b32 v200, v250, v188
	ds_bpermute_b32 v208, v250, v204
	ds_bpermute_b32 v216, v250, v212
	ds_bpermute_b32 v226, v250, v220
	ds_bpermute_b32 v242, v250, v238
	s_waitcnt lgkmcnt(7)
	v_add_f32_e32 v130, v130, v134
	s_waitcnt lgkmcnt(6)
	v_add_f32_e32 v138, v138, v142
	s_waitcnt lgkmcnt(5)
	v_add_f32_e32 v164, v164, v184
	s_waitcnt lgkmcnt(4)
	v_add_f32_e32 v188, v188, v200
	s_waitcnt lgkmcnt(3)
	v_add_f32_e32 v204, v204, v208
	s_waitcnt lgkmcnt(2)
	v_add_f32_e32 v212, v212, v216
	s_waitcnt lgkmcnt(1)
	v_add_f32_e32 v220, v220, v226
	s_waitcnt lgkmcnt(0)
	v_add_f32_e32 v238, v238, v242
	s_and_b64 s[10:11], s[6:7], s[24:25]
	s_mov_b64 s[12:13], 0x800
	s_and_saveexec_b64 s[0:1], s[10:11]
	s_cbranch_execz .Lepi2_done
	s_mov_b64 vcc, 0x2800
	global_store_dword v[168:169], v130, off
	v_lshl_add_u64 v[168:169], v[168:169], 0, s[12:13]
	global_store_dword v[168:169], v138, off
	v_lshl_add_u64 v[168:169], v[168:169], 0, s[12:13]
	global_store_dword v[168:169], v164, off
	v_lshl_add_u64 v[168:169], v[168:169], 0, s[12:13]
	global_store_dword v[168:169], v188, off
	v_lshl_add_u64 v[168:169], v[168:169], 0, vcc
	global_store_dword v[168:169], v204, off
	v_lshl_add_u64 v[168:169], v[168:169], 0, s[12:13]
	global_store_dword v[168:169], v212, off
	v_lshl_add_u64 v[168:169], v[168:169], 0, s[12:13]
	global_store_dword v[168:169], v220, off
	v_lshl_add_u64 v[168:169], v[168:169], 0, s[12:13]
	global_store_dword v[168:169], v238, off

; __device__ __forceinline__ float bflo(unsigned w) { return __uint_as_float(w << 16); }
; __device__ __forceinline__ float bfhi(unsigned w) { return __uint_as_float(w & 0xffff0000u); }
; __device__ __forceinline__ unsigned pk2(float lo, float hi) { return pg8::cvt_pk_bf16(lo, hi); }
; __device__ __forceinline__ void prep_row(const float* xrow, bf16* orow, float* ssq, int lane) {
;     const f32x4* xr = (const f32x4*)xrow + lane;
;     f32x4 v[8]; float s = 0.f;
; #pragma unroll
;     for (int j = 0; j < 8; ++j) { v[j] = __builtin_nontemporal_load(xr + 64 * j);
;         v2u w; w.x = pk2(v[j].x, v[j].y); w.y = pk2(v[j].z, v[j].w); ((v2u*)orow + lane)[64 * j] = w;
;         const float a0 = bflo(w.x), a1 = bfhi(w.x), a2 = bflo(w.y), a3 = bfhi(w.y); s += (a0 * a0 + a1 * a1) + (a2 * a2 + a3 * a3); }
;     s = wave_sum(s);
;     if (lane < 32) ssq[lane] = (lane == 0) ? s : 0.f;
; }
.LBB0_550:
	v_add_co_u32_e32 v18, vcc, 0xfffff000, v6
	v_lshl_add_u64 v[20:21], s[42:43], 0, v[4:5]
	s_nop 0
	v_addc_co_u32_e32 v19, vcc, -1, v7, vcc
	s_waitcnt lgkmcnt(0)
	v_add_co_u32_e32 v20, vcc, 0x27200000, v20
	s_nop 1
	v_addc_co_u32_e32 v21, vcc, 0, v21, vcc
	global_load_dwordx4 v[36:39], v[18:19], off offset:-3072 nt
	global_load_dwordx4 v[40:43], v[18:19], off offset:-2048 nt
	global_load_dwordx4 v[44:47], v[18:19], off offset:-1024 nt
	global_load_dwordx4 v[48:51], v[6:7], off offset:-4096 nt
	global_load_dwordx4 v[52:55], v[6:7], off offset:-3072 nt
	global_load_dwordx4 v[56:59], v[6:7], off offset:-2048 nt
	global_load_dwordx4 v[60:63], v[6:7], off offset:-1024 nt
	global_load_dwordx4 v[64:67], v[6:7], off nt
	s_waitcnt vmcnt(7)
	v_cvt_pk_bf16_f32 v22, v36, v37
	v_cvt_pk_bf16_f32 v23, v38, v39
	global_store_dwordx2 v[20:21], v[22:23], off
	v_lshlrev_b32_e32 v13, 16, v22
	v_and_b32_e32 v22, 0xffff0000, v22
	v_lshlrev_b32_e32 v34, 16, v23
	v_and_b32_e32 v23, 0xffff0000, v23
	v_mul_f32_e32 v22, v22, v22
	v_mul_f32_e32 v23, v23, v23
	v_fmac_f32_e32 v22, v13, v13
	v_fmac_f32_e32 v23, v34, v34
	v_add_f32_e32 v13, v22, v23
	s_waitcnt vmcnt(7)
	v_cvt_pk_bf16_f32 v24, v40, v41
	v_cvt_pk_bf16_f32 v25, v42, v43
	global_store_dwordx2 v[20:21], v[24:25], off offset:512
	v_lshlrev_b32_e32 v22, 16, v24
	v_and_b32_e32 v23, 0xffff0000, v24
	v_lshlrev_b32_e32 v24, 16, v25
	v_and_b32_e32 v25, 0xffff0000, v25
	v_mul_f32_e32 v23, v23, v23
	v_mul_f32_e32 v25, v25, v25
	v_fmac_f32_e32 v23, v22, v22
	v_fmac_f32_e32 v25, v24, v24
	v_add_f32_e32 v22, v23, v25
	v_add_f32_e32 v13, v13, v22
	s_waitcnt vmcnt(7)
	v_cvt_pk_bf16_f32 v18, v44, v45
	v_cvt_pk_bf16_f32 v19, v46, v47
	global_store_dwordx2 v[20:21], v[18:19], off offset:1024
	v_lshlrev_b32_e32 v22, 16, v18
	v_and_b32_e32 v18, 0xffff0000, v18
	v_lshlrev_b32_e32 v23, 16, v19
	v_and_b32_e32 v19, 0xffff0000, v19
	v_mul_f32_e32 v18, v18, v18
	v_mul_f32_e32 v19, v19, v19
	v_fmac_f32_e32 v18, v22, v22
	v_fmac_f32_e32 v19, v23, v23
	v_add_f32_e32 v18, v18, v19
	v_add_f32_e32 v13, v13, v18
	s_waitcnt vmcnt(7)
	v_cvt_pk_bf16_f32 v26, v48, v49
	v_cvt_pk_bf16_f32 v27, v50, v51
	global_store_dwordx2 v[20:21], v[26:27], off offset:1536
	v_and_b32_e32 v19, 0xffff0000, v26
	v_and_b32_e32 v23, 0xffff0000, v27
	v_lshlrev_b32_e32 v18, 16, v26
	v_lshlrev_b32_e32 v22, 16, v27
	v_mul_f32_e32 v19, v19, v19
	v_mul_f32_e32 v23, v23, v23
	v_fmac_f32_e32 v19, v18, v18
	v_fmac_f32_e32 v23, v22, v22
	v_add_f32_e32 v18, v19, v23
	v_add_f32_e32 v13, v13, v18
	s_waitcnt vmcnt(7)
	v_cvt_pk_bf16_f32 v28, v52, v53
	v_cvt_pk_bf16_f32 v29, v54, v55
	global_store_dwordx2 v[20:21], v[28:29], off offset:2048
	v_and_b32_e32 v19, 0xffff0000, v28
	v_and_b32_e32 v23, 0xffff0000, v29
	v_lshlrev_b32_e32 v18, 16, v28
	v_lshlrev_b32_e32 v22, 16, v29
	v_mul_f32_e32 v19, v19, v19
	v_mul_f32_e32 v23, v23, v23
	v_fmac_f32_e32 v19, v18, v18
	v_fmac_f32_e32 v23, v22, v22
	v_add_f32_e32 v18, v19, v23
	v_add_f32_e32 v13, v13, v18
	s_waitcnt vmcnt(7)
	v_cvt_pk_bf16_f32 v30, v56, v57
	v_cvt_pk_bf16_f32 v31, v58, v59
	global_store_dwordx2 v[20:21], v[30:31], off offset:2560
	v_and_b32_e32 v19, 0xffff0000, v30
	v_and_b32_e32 v23, 0xffff0000, v31
	v_lshlrev_b32_e32 v18, 16, v30
	v_lshlrev_b32_e32 v22, 16, v31
	v_mul_f32_e32 v19, v19, v19
	v_mul_f32_e32 v23, v23, v23
	v_fmac_f32_e32 v19, v18, v18
	v_fmac_f32_e32 v23, v22, v22
	v_add_f32_e32 v18, v19, v23
	v_add_f32_e32 v13, v13, v18
	s_waitcnt vmcnt(7)
	v_cvt_pk_bf16_f32 v32, v60, v61
	v_cvt_pk_bf16_f32 v33, v62, v63
	global_store_dwordx2 v[20:21], v[32:33], off offset:3072
	v_and_b32_e32 v19, 0xffff0000, v32
	v_and_b32_e32 v23, 0xffff0000, v33
	v_lshlrev_b32_e32 v18, 16, v32
	v_lshlrev_b32_e32 v22, 16, v33
	v_mul_f32_e32 v19, v19, v19
	v_mul_f32_e32 v23, v23, v23
	v_fmac_f32_e32 v19, v18, v18
	v_fmac_f32_e32 v23, v22, v22
	v_add_f32_e32 v18, v19, v23
	v_add_f32_e32 v13, v13, v18
	s_waitcnt vmcnt(7)
	v_cvt_pk_bf16_f32 v18, v64, v65
	v_cvt_pk_bf16_f32 v19, v66, v67
	v_and_b32_e32 v15, 0xffff0000, v18
	v_and_b32_e32 v17, 0xffff0000, v19
	v_lshlrev_b32_e32 v14, 16, v18
	v_lshlrev_b32_e32 v16, 16, v19
	v_mul_f32_e32 v15, v15, v15
	v_mul_f32_e32 v17, v17, v17
	v_fmac_f32_e32 v15, v14, v14
	v_fmac_f32_e32 v17, v16, v16
	v_add_f32_e32 v14, v15, v17
	v_add_f32_e32 v13, v13, v14
	ds_bpermute_b32 v14, v0, v13
	global_store_dwordx2 v[20:21], v[18:19], off offset:3584
	s_waitcnt lgkmcnt(0)
	v_add_f32_e32 v13, v13, v14
	ds_bpermute_b32 v14, v8, v13
	s_waitcnt lgkmcnt(0)
	v_add_f32_e32 v13, v13, v14
	ds_bpermute_b32 v14, v9, v13
	s_waitcnt lgkmcnt(0)
	v_add_f32_e32 v13, v13, v14
	ds_bpermute_b32 v14, v10, v13
	s_waitcnt lgkmcnt(0)
	v_add_f32_e32 v13, v13, v14
	ds_bpermute_b32 v14, v11, v13
	s_waitcnt lgkmcnt(0)
	v_add_f32_e32 v13, v13, v14
	ds_bpermute_b32 v14, v12, v13
	s_and_saveexec_b64 s[12:13], s[6:7]
	s_cbranch_execz .LBB0_549
	s_waitcnt lgkmcnt(0)
	v_add_f32_e32 v13, v13, v14
	v_cndmask_b32_e64 v13, 0, v13, s[8:9]
	v_lshl_add_u64 v[14:15], s[42:43], 0, v[2:3]
	global_store_dword v[14:15], v13, off
	s_branch .LBB0_549
